# PV1 k-step-1 V fragment reads issued after the k-step-0 MFMAs instead of up front (8 reads up front, 2 per MFMA after)
# speedup vs baseline: 1.0007x; 1.0007x over previous
; #define VWAIT(N, f) asm volatile("s_waitcnt lgkmcnt(" #N ")" : "+v"(f.l0), "+v"(f.h0), "+v"(f.l1), "+v"(f.h1) :: "memory")
; template <int H, int D0> __device__ __forceinline__ VFrag pv_rd(int vb) {
;   VFrag f; f.l0 = tr_read<v_rd_off(D0, 2 * H, 0)>(vb); f.h0 = tr_read<v_rd_off(D0, 2 * H, 1)>(vb); f.l1 = tr_read<v_rd_off(D0, 2 * H + 1, 0)>(vb); f.h1 = tr_read<v_rd_off(D0, 2 * H + 1, 1)>(vb); return f;
; }
; __device__ __forceinline__ void pv_mma(f32x16& od, VFrag& f, bf16x8 paL, bf16x8 paH) {
;     ...
;   od = __builtin_amdgcn_mfma_f32_32x32x16_bf16(paL, PK(f.l0, f.h0), od, 0, 0, 0);
;   od = __builtin_amdgcn_mfma_f32_32x32x16_bf16(paH, PK(f.l1, f.h1), od, 0, 0, 0);
;     ...
; }
; template <int H> __device__ __forceinline__ void pv_half(f32x16* o, int vb, bf16x8 paL, bf16x8 paH) {
;   VFrag fa = pv_rd<H, 0>(vb), fb = pv_rd<H, 1>(vb);
;   VWAIT(4, fa); pv_mma(o[0], fa, paL, paH);
;   fa = pv_rd<H, 2>(vb);
;   VWAIT(4, fb); pv_mma(o[1], fb, paL, paH);
;   fb = pv_rd<H, 3>(vb);
;   VWAIT(4, fa); pv_mma(o[2], fa, paL, paH);
;   VWAIT(0, fb); pv_mma(o[3], fb, paL, paH);
; }
.LBB0_518:
	v_fma_f32 v202, v197, v0, v198
	v_fma_f32 v0, v202, v200, v201
	v_fma_f32 v202, v0, v249, v91
	ds_read_b64_tr_b16 v[204:205], v181 offset:0x2000
	ds_read_b64_tr_b16 v[206:207], v181 offset:0x2800
	ds_read_b64_tr_b16 v[82:83], v181 offset:0x2200
	ds_read_b64_tr_b16 v[84:85], v181 offset:0x2a00
	ds_read_b64_tr_b16 v[212:213], v181 offset:0x2400
	ds_read_b64_tr_b16 v[214:215], v181 offset:0x2c00
	ds_read_b64_tr_b16 v[216:217], v181 offset:0x2600
	ds_read_b64_tr_b16 v[218:219], v181 offset:0x2e00
	v_exp_f32_e32 v74, v74
	v_exp_f32_e32 v75, v75
	s_add_i32 s87, s87, 2
	s_and_b64 vcc, exec, s[62:63]
	s_waitcnt lgkmcnt(6)
	v_mfma_f32_32x32x16_bf16 v[50:65], v[66:69], v[204:207], v[50:65]
	ds_read_b64_tr_b16 v[208:209], v181 offset:0x3000
	ds_read_b64_tr_b16 v[210:211], v181 offset:0x3800
	v_exp_f32_e32 v76, v76
	v_exp_f32_e32 v77, v77
	v_add_f32_e32 v163, v74, v163
	v_add_f32_e32 v163, v75, v163
	s_waitcnt lgkmcnt(6)
	v_mfma_f32_32x32x16_bf16 v[34:49], v[66:69], v[82:85], v[34:49]
	ds_read_b64_tr_b16 v[86:87], v181 offset:0x3200
	ds_read_b64_tr_b16 v[88:89], v181 offset:0x3a00
	v_exp_f32_e32 v78, v78
	v_exp_f32_e32 v79, v79
	v_add_f32_e32 v163, v76, v163
	v_add_f32_e32 v163, v77, v163
	v_cvt_pk_bf16_f32 v70, v74, v75
	v_cvt_pk_bf16_f32 v71, v76, v77
	s_waitcnt lgkmcnt(6)
	v_mfma_f32_32x32x16_bf16 v[18:33], v[66:69], v[212:215], v[18:33]
	ds_read_b64_tr_b16 v[204:205], v181 offset:0x3400
	ds_read_b64_tr_b16 v[206:207], v181 offset:0x3c00
	v_exp_f32_e32 v80, v80
	v_exp_f32_e32 v81, v81
	v_add_f32_e32 v163, v78, v163
	v_add_f32_e32 v163, v79, v163
	s_waitcnt lgkmcnt(6)
	v_mfma_f32_32x32x16_bf16 v[2:17], v[66:69], v[216:219], v[2:17]
	ds_read_b64_tr_b16 v[82:83], v181 offset:0x3600
	ds_read_b64_tr_b16 v[84:85], v181 offset:0x3e00
	v_cvt_pk_bf16_f32 v72, v78, v79
	v_add_f32_e32 v163, v80, v163
	v_add_f32_e32 v163, v81, v163
	v_cvt_pk_bf16_f32 v73, v80, v81
	s_nop 1
	v_permlane32_swap_b32_e32 v70, v72
	v_permlane32_swap_b32_e32 v71, v73
	s_nop 1
	s_waitcnt vmcnt(0) lgkmcnt(0)
	v_mfma_f32_32x32x16_bf16 v[50:65], v[70:73], v[208:211], v[50:65]
	s_barrier
	v_mfma_f32_32x32x16_bf16 v[34:49], v[70:73], v[86:89], v[34:49]
	v_mfma_f32_32x32x16_bf16 v[18:33], v[70:73], v[204:207], v[18:33]
	v_mfma_f32_32x32x16_bf16 v[2:17], v[70:73], v[82:85], v[2:17]
	v_fma_f32 v197, v202, v93, v163
	s_cbranch_vccnz .LBB0_542

; #define VWAIT(N, f) asm volatile("s_waitcnt lgkmcnt(" #N ")" : "+v"(f.l0), "+v"(f.h0), "+v"(f.l1), "+v"(f.h1) :: "memory")
; template <int H, int D0> __device__ __forceinline__ VFrag pv_rd(int vb) {
;   VFrag f; f.l0 = tr_read<v_rd_off(D0, 2 * H, 0)>(vb); f.h0 = tr_read<v_rd_off(D0, 2 * H, 1)>(vb); f.l1 = tr_read<v_rd_off(D0, 2 * H + 1, 0)>(vb); f.h1 = tr_read<v_rd_off(D0, 2 * H + 1, 1)>(vb); return f;
; }
; __device__ __forceinline__ void pv_mma(f32x16& od, VFrag& f, bf16x8 paL, bf16x8 paH) {
;     ...
;   od = __builtin_amdgcn_mfma_f32_32x32x16_bf16(paL, PK(f.l0, f.h0), od, 0, 0, 0);
;   od = __builtin_amdgcn_mfma_f32_32x32x16_bf16(paH, PK(f.l1, f.h1), od, 0, 0, 0);
;     ...
; }
; template <int H> __device__ __forceinline__ void pv_half(f32x16* o, int vb, bf16x8 paL, bf16x8 paH) {
;   VFrag fa = pv_rd<H, 0>(vb), fb = pv_rd<H, 1>(vb);
;   VWAIT(4, fa); pv_mma(o[0], fa, paL, paH);
;   fa = pv_rd<H, 2>(vb);
;   VWAIT(4, fb); pv_mma(o[1], fb, paL, paH);
;   fb = pv_rd<H, 3>(vb);
;   VWAIT(4, fa); pv_mma(o[2], fa, paL, paH);
;   VWAIT(0, fb); pv_mma(o[3], fb, paL, paH);
; }
.LBB0_531:
	ds_read_b64_tr_b16 v[90:91], v175 offset:0x2000
	ds_read_b64_tr_b16 v[92:93], v175 offset:0x2800
	ds_read_b64_tr_b16 v[82:83], v175 offset:0x2200
	ds_read_b64_tr_b16 v[84:85], v175 offset:0x2a00
	ds_read_b64_tr_b16 v[202:203], v175 offset:0x2400
	ds_read_b64_tr_b16 v[204:205], v175 offset:0x2c00
	ds_read_b64_tr_b16 v[206:207], v175 offset:0x2600
	ds_read_b64_tr_b16 v[208:209], v175 offset:0x2e00
	v_exp_f32_e32 v74, v74
	v_exp_f32_e32 v75, v75
	s_cmp_lt_u32 s87, s79
	s_cselect_b64 s[64:65], -1, 0
	s_cmp_ge_u32 s87, s79
	s_cselect_b64 s[62:63], -1, 0
	s_and_b64 vcc, exec, s[62:63]
	s_waitcnt lgkmcnt(6)
	v_mfma_f32_32x32x16_bf16 v[50:65], v[66:69], v[90:93], v[50:65]
	ds_read_b64_tr_b16 v[94:95], v175 offset:0x3000
	ds_read_b64_tr_b16 v[96:97], v175 offset:0x3800
	v_exp_f32_e32 v76, v76
	v_exp_f32_e32 v77, v77
	v_add_f32_e32 v201, v74, v201
	v_add_f32_e32 v201, v75, v201
	s_waitcnt lgkmcnt(6)
	v_mfma_f32_32x32x16_bf16 v[34:49], v[66:69], v[82:85], v[34:49]
	ds_read_b64_tr_b16 v[86:87], v175 offset:0x3200
	ds_read_b64_tr_b16 v[88:89], v175 offset:0x3a00
	v_exp_f32_e32 v78, v78
	v_exp_f32_e32 v79, v79
	v_add_f32_e32 v201, v76, v201
	v_add_f32_e32 v201, v77, v201
	v_cvt_pk_bf16_f32 v70, v74, v75
	v_cvt_pk_bf16_f32 v71, v76, v77
	s_waitcnt lgkmcnt(6)
	v_mfma_f32_32x32x16_bf16 v[18:33], v[66:69], v[202:205], v[18:33]
	ds_read_b64_tr_b16 v[90:91], v175 offset:0x3400
	ds_read_b64_tr_b16 v[92:93], v175 offset:0x3c00
	v_exp_f32_e32 v80, v80
	v_exp_f32_e32 v81, v81
	v_add_f32_e32 v201, v78, v201
	v_add_f32_e32 v201, v79, v201
	s_waitcnt lgkmcnt(6)
	v_mfma_f32_32x32x16_bf16 v[2:17], v[66:69], v[206:209], v[2:17]
	ds_read_b64_tr_b16 v[82:83], v175 offset:0x3600
	ds_read_b64_tr_b16 v[84:85], v175 offset:0x3e00
	v_cvt_pk_bf16_f32 v72, v78, v79
	v_add_f32_e32 v201, v80, v201
	v_add_f32_e32 v201, v81, v201
	v_cvt_pk_bf16_f32 v73, v80, v81
	s_nop 1
	v_permlane32_swap_b32_e32 v70, v72
	v_permlane32_swap_b32_e32 v71, v73
	s_nop 1
	s_waitcnt vmcnt(0) lgkmcnt(0)
	v_mfma_f32_32x32x16_bf16 v[50:65], v[70:73], v[94:97], v[50:65]
	s_barrier
	v_mfma_f32_32x32x16_bf16 v[34:49], v[70:73], v[86:89], v[34:49]
	v_mfma_f32_32x32x16_bf16 v[18:33], v[70:73], v[90:93], v[18:33]
	v_mfma_f32_32x32x16_bf16 v[2:17], v[70:73], v[82:85], v[2:17]
	s_cbranch_vccnz .LBB0_533
	s_mov_b32 m0, s82
	s_nop 0
	global_load_lds_dwordx4 v152, s[18:19]
	s_mov_b32 m0, s83
	s_nop 0
	global_load_lds_dwordx4 v153, s[18:19]
	s_add_u32 s18, s18, 0x18000
	s_addc_u32 s19, s19, 0
